# mixer-even: item order rotated by bx%3 (desynchronises HBM bursts across workgroups), on stack10
# baseline (speedup 1.0000x reference)
; __device__ __forceinline__ void mixa_item(const Args& A, int li, int item, LAS unsigned char* lds, int tid, int lane, int wave) {
;     const int chunk = item >> 1, gh = item & 1, row0 = chunk * 128;
;     const bf16_t* UV = (const bf16_t*)(A.ws + WS_UV); bf16_t* CAT = (bf16_t*)(A.ws + WS_CAT);
;     const float* vg = A.in[8] + li * 512; const float* vb = A.in[9] + li * 512; const float* spb = A.in[7] + li * 8 * 128;
;     const bf16_t* spw = (const bf16_t*)(A.ws + WS_SPW) + (size_t)li * 8 * 128 * 128;
;     {
;         const int l15 = lane & 15, l4 = lane >> 4;
;         f32x4 gA[2][2], bA[2][2];
; #pragma unroll
;         for (int i = 0; i < 2; ++i) { const int chn = (l15 + 16 * (2 * gh + i)) * 8;
;             gA[i][0] = *(const f32x4*)(vg + chn); gA[i][1] = *(const f32x4*)(vg + chn + 4); bA[i][0] = *(const f32x4*)(vb + chn); bA[i][1] = *(const f32x4*)(vb + chn + 4); }
;         u32x4 w[4][4];
; #pragma unroll
;         for (int it = 0; it < 4; ++it)
; #pragma unroll
;             for (int i = 0; i < 4; ++i) w[it][i] = *(const u32x4*)(UV + (size_t)(row0 + wave * 16 + it * 4 + l4) * 1024 + 512 + (l15 + 16 * i) * 8);
;         u32x4 wsel[4][2];
; #pragma unroll
;         for (int it = 0; it < 4; ++it)
; #pragma unroll
;             for (int i = 0; i < 2; ++i) wsel[it][i] = *(const u32x4*)(UV + (size_t)(row0 + wave * 16 + it * 4 + l4) * 1024 + 512 + (l15 + 16 * (2 * gh + i)) * 8);
; #pragma unroll
;         for (int it = 0; it < 4; ++it) {
;             const int q = wave * 16 + it * 4 + l4; float s1 = 0.f, s2 = 0.f;
; #pragma unroll
;             for (int i = 0; i < 4; ++i)
; #pragma unroll
;                 for (int e = 0; e < 4; ++e) { const float a = bf_lo(w[it][i][e]), b = bf_hi(w[it][i][e]); s1 += a + b; s2 += a * a + b * b; }
;             s1 = sum16(s1); s2 = sum16(s2);
;             const float mean = s1 * (1.0f / 512.0f), rstd = __builtin_amdgcn_rsqf(fmaxf(s2 * (1.0f / 512.0f) - mean * mean, 0.f) + 1e-6f);
; #pragma unroll
;             for (int i = 0; i < 2; ++i) {
;                 const u32x4 ww = wsel[it][i]; u32x4 o;
; #pragma unroll
;                 for (int e = 0; e < 4; ++e) { const int h2 = e >> 1, k2 = (e & 1) * 2;
;                     const float a = (bf_lo(ww[e]) - mean) * rstd * gA[i][h2][k2] + bA[i][h2][k2], b = (bf_hi(ww[e]) - mean) * rstd * gA[i][h2][k2 + 1] + bA[i][h2][k2 + 1];
;                     o[e] = cvt_pk_bf16(a, b); }
.LBB0_433:
	s_and_b64 vcc, exec, s[0:1]
	s_cbranch_vccz .LBB0_480
	v_readlane_b32 s0, v252, 51
	v_readlane_b32 s1, v252, 52
	s_andn2_b64 vcc, exec, s[0:1]
	s_cbranch_vccnz .LBB0_480
	v_readlane_b32 s0, v254, 24
	v_readlane_b32 s1, v254, 25
	v_readlane_b32 s4, v254, 52
	v_readlane_b32 s68, v252, 31
	s_mov_b32 s3, s1
	s_lshl_b32 s2, s4, 9
	v_readlane_b32 s69, v252, 32
	s_lshl_b64 s[48:49], s[2:3], 2
	v_readlane_b32 s70, v252, 33
	v_readlane_b32 s71, v252, 34
	v_readlane_b32 s72, v252, 35
	v_readlane_b32 s73, v252, 36
	v_readlane_b32 s74, v252, 37
	v_readlane_b32 s75, v252, 38
	v_readlane_b32 s76, v252, 39
	v_readlane_b32 s77, v252, 40
	v_readlane_b32 s78, v252, 41
	v_readlane_b32 s79, v252, 42
	s_mov_b64 s[52:53], s[68:69]
	s_add_u32 s8, s52, s48
	v_readlane_b32 s80, v252, 43
	v_readlane_b32 s81, v252, 44
	v_readlane_b32 s82, v252, 45
	v_readlane_b32 s83, v252, 46
	s_mov_b64 s[54:55], s[70:71]
	s_addc_u32 s9, s53, s49
	s_mov_b64 s[56:57], s[72:73]
	s_mov_b64 s[58:59], s[74:75]
	s_mov_b64 s[60:61], s[76:77]
	s_mov_b64 s[62:63], s[78:79]
	s_add_u32 s16, s54, s48
	v_readlane_b32 s68, v252, 15
	s_addc_u32 s17, s55, s49
	s_lshl_b32 s2, s4, 10
	v_writelane_b32 v254, s0, 24
	v_readlane_b32 s82, v252, 29
	v_readlane_b32 s83, v252, 30
	v_writelane_b32 v254, s1, 25
	s_lshl_b64 s[0:1], s[2:3], 2
	s_mov_b64 s[22:23], s[82:83]
	s_add_u32 s26, s22, s0
	v_lshrrev_b32_e32 v6, 4, v168
	v_readlane_b32 s2, v254, 55
	s_addc_u32 s27, s23, s1
	s_movk_i32 s1, 0x2a0
	s_waitcnt vmcnt(0)
	v_lshl_or_b32 v113, s2, 4, v6
	s_lshl_b32 s0, s4, 18
	v_mul_lo_u32 v9, v113, s1
	v_readlane_b32 s1, v254, 0
	s_add_u32 s0, s1, s0
	v_readlane_b32 s1, v254, 1
	v_bfe_u32 v2, v160, 2, 2
	s_addc_u32 s1, s1, 0
	v_lshl_or_b32 v2, v6, 2, v2
	s_and_b32 s4, s5, 0xffffff80
	v_lshlrev_b32_e32 v3, 3, v168
	v_mul_u32_u24_e32 v2, 0x2a0, v2
	v_and_b32_e32 v3, 24, v3
	s_add_i32 s4, s4, 0
	v_add3_u32 v115, s4, v2, v3
	v_lshlrev_b32_e32 v2, 3, v6
	v_mov_b32_e32 v3, v177
	v_lshl_add_u64 v[4:5], s[0:1], 0, v[2:3]
	v_readlane_b32 s0, v253, 49
	s_movk_i32 s10, 0x980
	v_readlane_b32 s1, v253, 50
	v_cmp_gt_i32_e64 s[38:39], s10, v160
	s_movk_i32 s10, 0x780
	v_lshl_add_u64 v[116:117], s[0:1], 0, v[2:3]
	v_readlane_b32 s0, v254, 2
	v_cmp_gt_i32_e64 s[40:41], s10, v160
	s_movk_i32 s10, 0x580
	v_readlane_b32 s1, v254, 3
	v_cmp_gt_i32_e64 s[42:43], s10, v160
	s_movk_i32 s10, 0x380
	s_ashr_i32 s3, s5, 7
	v_lshl_add_u64 v[118:119], s[0:1], 0, v[2:3]
	v_lshlrev_b32_e32 v155, 4, v160
	v_readlane_b32 s0, v253, 53
	v_cmp_gt_i32_e64 s[44:45], s10, v160
	s_movk_i32 s10, 0x180
	v_and_b32_e32 v2, 0x3f0, v155
	v_readlane_b32 s1, v253, 54
	v_cmp_gt_i32_e64 s[46:47], s10, v160
	s_add_u32 s10, s58, s48
	v_and_b32_e32 v25, 0xff, v160
	v_lshl_add_u64 v[120:121], s[0:1], 0, v[2:3]
	s_addc_u32 s11, s59, s49
	v_lshlrev_b32_e32 v2, 3, v25
	v_lshl_add_u64 v[122:123], s[10:11], 0, v[2:3]
	s_lshl_b32 s11, s2, 2
	s_and_b32 s10, s11, -16
	s_add_i32 s14, 0, 0x10000
	v_ashrrev_i32_e32 v157, 6, v161
	v_lshlrev_b32_e32 v11, 4, v161
	s_add_u32 s20, s60, s48
	v_or_b32_e32 v161, s11, v6
	s_movk_i32 s11, 0x810
	s_waitcnt lgkmcnt(0)
	v_and_b32_e32 v1, 15, v160
	s_addc_u32 s21, s61, s49
	v_mul_lo_u32 v6, v161, s11
	v_lshlrev_b32_e32 v112, 3, v1
	v_lshlrev_b32_e32 v0, 4, v1
	s_waitcnt lgkmcnt(0)
	v_and_or_b32 v114, s5, 64, v1
	s_movk_i32 s4, 0xd80
	v_add_u32_e32 v26, s14, v6
	s_add_u32 s22, s62, s48
	v_lshlrev_b32_e32 v6, 2, v1
	v_mov_b32_e32 v1, v177
	s_movk_i32 s0, 0xf80
	v_cmp_gt_i32_e64 s[6:7], s4, v160
	s_movk_i32 s4, 0xb80
	s_addc_u32 s23, s63, s49
	v_lshl_add_u64 v[124:125], s[20:21], 0, v[0:1]
	s_lshr_b64 s[20:21], s[18:19], 1
	s_lshr_b32 s11, s19, 1
	v_ashrrev_i32_e32 v156, 6, v160
	v_cmp_gt_i32_e64 s[0:1], s0, v160
	v_cmp_gt_i32_e64 s[4:5], s4, v160
	v_add_u32_e32 v160, s14, v2
	s_mul_i32 s11, s11, 0xf800
	s_mul_hi_u32 s14, s20, 0xf800
	s_add_i32 s14, s14, s11
	s_mul_i32 s11, s20, 0xf800
	s_add_u32 s20, s56, s11
	s_addc_u32 s21, s57, s14
	s_lshl_b32 s2, s2, 12
	s_and_b32 s2, s2, 0xffffc000
	v_add_u32_e32 v7, 0, v0
	v_lshlrev_b32_e32 v13, 4, v162
	v_lshlrev_b32_e32 v15, 4, v163
	v_lshlrev_b32_e32 v17, 4, v164
	v_lshlrev_b32_e32 v19, 4, v165
	v_lshlrev_b32_e32 v21, 4, v166
	v_lshlrev_b32_e32 v24, 4, v167
	v_or_b32_e32 v8, 64, v6
	v_or_b32_e32 v10, 0x80, v6
	v_or_b32_e32 v12, 0xc0, v6
	v_or_b32_e32 v14, 0x100, v6
	v_or_b32_e32 v16, 0x140, v6
	v_or_b32_e32 v18, 0x180, v6
	v_or_b32_e32 v20, 0x1c0, v6
	v_lshlrev_b32_e32 v22, 8, v114
	v_mov_b32_e32 v23, v177
	s_add_i32 s2, s2, 0
	v_add_u32_e32 v148, 0x12600, v115
	v_add_u32_e32 v149, 0x12620, v115
	v_add_u32_e32 v150, 0x12640, v115
	v_add_u32_e32 v151, 0x12660, v115
	v_or_b32_e32 v152, 16, v114
	v_or_b32_e32 v153, 32, v114
	v_or_b32_e32 v154, 48, v114
	v_ashrrev_i32_e32 v158, 6, v162
	v_ashrrev_i32_e32 v159, 6, v163
	v_ashrrev_i32_e32 v168, 6, v164
	v_ashrrev_i32_e32 v169, 6, v165
	v_ashrrev_i32_e32 v170, 6, v166
	v_ashrrev_i32_e32 v171, 6, v167
	v_lshl_add_u64 v[126:127], s[22:23], 0, v[0:1]
	v_lshl_add_u64 v[128:129], v[4:5], 0, v[22:23]
	v_lshl_add_u64 v[130:131], s[20:21], 0, v[2:3]
	v_lshl_add_u32 v162, v25, 2, s2
	v_add_u32_e32 v163, v7, v9
	v_add_u32_e32 v164, 0, v11
	v_add_u32_e32 v165, 0, v13
	v_add_u32_e32 v166, 0, v15
	v_add_u32_e32 v167, 0, v17
	v_add_u32_e32 v172, 0, v19
	v_add_u32_e32 v173, 0, v21
	v_add_u32_e32 v174, 0, v24
	v_add_u32_e32 v175, v26, v0
	v_lshlrev_b32_e32 v132, 1, v6
	v_lshlrev_b32_e32 v134, 1, v8
	v_lshlrev_b32_e32 v136, 1, v10
	v_lshlrev_b32_e32 v138, 1, v12
	v_lshlrev_b32_e32 v140, 1, v14
	v_lshlrev_b32_e32 v142, 1, v16
	v_lshlrev_b32_e32 v144, 1, v18
	v_lshlrev_b32_e32 v146, 1, v20
	s_mov_b32 s2, s67
	s_mov_b32 s101, 0
	v_readlane_b32 s100, v252, 10
	s_cmp_lg_u32 s100, 0x100
	s_cbranch_scc1 .Lxr_plain
	s_mul_hi_u32 s100, s67, 0x55555556
	s_mul_i32 s100, s100, 3
	s_sub_i32 s100, s67, s100
	s_lshl_b32 s100, s100, 8
	s_add_i32 s2, s67, s100
	s_mov_b32 s101, 3
.Lxr_plain:
	v_readlane_b32 s69, v252, 16
	v_readlane_b32 s70, v252, 17
	v_readlane_b32 s71, v252, 18
	v_readlane_b32 s72, v252, 19
	v_readlane_b32 s73, v252, 20
	v_readlane_b32 s74, v252, 21
	v_readlane_b32 s75, v252, 22
	v_readlane_b32 s76, v252, 23
	v_readlane_b32 s77, v252, 24
	v_readlane_b32 s78, v252, 25
	v_readlane_b32 s79, v252, 26
	v_readlane_b32 s80, v252, 27
	v_readlane_b32 s81, v252, 28
	s_branch .LBB0_438

; __global__ void __launch_bounds__(NTHR, 2) mega_fwd(Args A) {
;     ...
;         if (even) { for (int it = bx; it < 768; it += G) {
.LBB0_437:
	s_cmp_eq_u32 s101, 0
	s_cbranch_scc1 .Lxr_lin
	s_add_i32 s101, s101, -1
	s_cmp_eq_u32 s101, 0
	s_cbranch_scc1 .LBB0_480
	s_add_i32 s2, s2, 0x100
	s_cmpk_gt_i32 s2, 0x2ff
	s_cbranch_scc0 .LBB0_438
	s_add_i32 s2, s2, 0xfffffd00
	s_branch .LBB0_438
